# FFN-up sample epilogue: group-6 wait counted past its 4 h-row stores (vmcnt(4)), on top of the store sinking
# baseline (speedup 1.0000x reference)
; __device__ __forceinline__ unsigned cvt_pk_bf16(float lo, float hi) { const bf16x2_t r = __builtin_convertvector((f32x2){lo, hi}, bf16x2_t); return __builtin_bit_cast(unsigned, r); }
; __device__ __forceinline__ float silu_f(float x) { return x * __builtin_amdgcn_rcpf(1.0f + __expf(-x)); }
;     __device__ __forceinline__ f32x4 conv4s(const f32x4 c4, const f32x4 pv, int t, const f32x4 w0, const f32x4 w1, const f32x4 w2, const f32x4 bsv) const {
;         f32x4 p1, p2;
; #pragma unroll
;         for (int e = 0; e < 4; ++e) { p1[e] = dpp_f<0x111>(0.f, c4[e]); p2[e] = dpp_f<0x112>(0.f, c4[e]); const float q1 = dpp_f<0x101>(0.f, pv[e]);
;             p1[e] = t == 0 ? q1 : p1[e]; p2[e] = t < 2 ? pv[e] : p2[e]; }
;         f32x4 uu = bsv + w2 * c4 + w1 * p1 + w0 * p2;
;         asm volatile("" : "+v"(uu));
;         return uu;
;     __device__ __forceinline__ void sample(f32x4 (&acc)[2][2][4][2], const Unit& u, int row0t, int wr, int wc, int fr, int fq) const {
;     ...
;             for (int k = 0; k < 4; ++k) { pv[k] = (f32x4){0.f, 0.f, 0.f, 0.f}; if (t < 2) pv[k] = *(const f32x4*)((const char*)st + stoff + (unsigned)(((16 * ai + 2 * (mp + k)) * 2 * DFF2 + DFF + 4 * n) * 4)); }
; #pragma unroll
;             for (int k = 0; k < 4; ++k) { const int m = mp + k;
;                 const f32x4 uu = conv4s(acc[ai][1][m][n], pv[k], t, w0, w1, w2, bsv);
;                 const f32x4 ua = acc[ai][0][m][n];
;                 u32x2 w; w.x = cvt_pk_bf16(silu_f(ua[0]) * uu[0], silu_f(ua[1]) * uu[1]); w.y = cvt_pk_bf16(silu_f(ua[2]) * uu[2], silu_f(ua[3]) * uu[3]);
;                 if ((step & 1) == 0) pend[m] = w;
;                 else { u32x4 o; if (n == 1) { o.x = pend[m].x; o.y = pend[m].y; o.z = w.x; o.w = w.y; } else { o.x = w.x; o.y = w.y; o.z = pend[m].x; o.w = pend[m].y; }
;                     *(u32x4*)((char*)act + rowoff0 + (unsigned)((ai * HALF + m * 16) * DFF * 2) + (unsigned)(ca * 2)) = o; }
.Lspp_6:
	s_or_b64 exec, exec, s[100:101]
	s_nop 4
	v_mov_b32_dpp v114, v206 row_shl:1 row_mask:0xf bank_mask:0xf
	v_pk_mul_f32 v[110:111], v[110:111], v[112:113]
	v_mov_b32_dpp v115, v67 row_shr:2 row_mask:0xf bank_mask:0xf
	v_add_f32_e32 v18, 1.0, v18
	v_rcp_f32_e32 v112, v18
	v_mul_f32_e32 v18, 0xbfb8aa3b, v109
	v_exp_f32_e32 v18, v18
	v_pk_mul_f32 v[110:111], v[110:111], v[160:161]
	v_cndmask_b32_e64 v115, v115, v207, s[4:5]
	v_cvt_pk_bf16_f32 v111, v110, v111
	v_add_f32_e32 v18, 1.0, v18
	v_rcp_f32_e32 v113, v18
	v_mul_f32_e32 v18, 0xbfb8aa3b, v106
	v_exp_f32_e32 v18, v18
	v_pk_mul_f32 v[108:109], v[108:109], v[112:113]
	s_nop 0
	v_pk_mul_f32 v[108:109], v[108:109], v[158:159]
	v_add_f32_e32 v18, 1.0, v18
	v_cvt_pk_bf16_f32 v110, v108, v109
	v_rcp_f32_e32 v108, v18
	v_mul_f32_e32 v18, 0xbfb8aa3b, v107
	v_exp_f32_e32 v18, v18
	s_nop 0
	s_nop 0
	v_add_f32_e32 v18, 1.0, v18
	v_rcp_f32_e32 v109, v18
	v_mul_f32_e32 v18, 0xbfb8aa3b, v104
	v_exp_f32_e32 v18, v18
	v_mov_b32_dpp v112, v205 row_shl:1 row_mask:0xf bank_mask:0xf bound_ctrl:1
	v_pk_mul_f32 v[106:107], v[106:107], v[108:109]
	v_mov_b32_dpp v113, v66 row_shr:2 row_mask:0xf bank_mask:0xf bound_ctrl:1
	v_add_f32_e32 v18, 1.0, v18
	v_rcp_f32_e32 v108, v18
	v_mul_f32_e32 v18, 0xbfb8aa3b, v105
	v_exp_f32_e32 v18, v18
	v_pk_mul_f32 v[106:107], v[106:107], v[156:157]
	v_add_f32_e32 v18, 1.0, v18
	v_rcp_f32_e32 v109, v18
	v_mul_f32_e32 v18, 0xbfb8aa3b, v102
	v_exp_f32_e32 v18, v18
	v_cvt_pk_bf16_f32 v107, v106, v107
	v_pk_mul_f32 v[104:105], v[104:105], v[108:109]
	s_nop 0
	v_pk_mul_f32 v[104:105], v[104:105], v[154:155]
	v_add_f32_e32 v18, 1.0, v18
	v_cvt_pk_bf16_f32 v106, v104, v105
	v_rcp_f32_e32 v104, v18
	v_mul_f32_e32 v18, 0xbfb8aa3b, v103
	v_exp_f32_e32 v18, v18
	v_mov_b32_dpp v108, v204 row_shl:1 row_mask:0xf bank_mask:0xf bound_ctrl:1
	s_nop 0
	v_add_f32_e32 v18, 1.0, v18
	v_rcp_f32_e32 v105, v18
	v_mul_f32_e32 v18, 0xbfb8aa3b, v100
	v_exp_f32_e32 v18, v18
	v_mov_b32_dpp v109, v65 row_shr:2 row_mask:0xf bank_mask:0xf bound_ctrl:1
	v_pk_mul_f32 v[102:103], v[102:103], v[104:105]
	v_cndmask_b32_e64 v109, v109, v205, s[4:5]
	v_add_f32_e32 v18, 1.0, v18
	v_rcp_f32_e32 v104, v18
	v_mul_f32_e32 v18, 0xbfb8aa3b, v101
	v_exp_f32_e32 v18, v18
	v_pk_mul_f32 v[102:103], v[102:103], v[152:153]
	v_add_f32_e32 v18, 1.0, v18
	v_rcp_f32_e32 v105, v18
	v_mul_lo_u32 v18, v174, s2
	v_cvt_pk_bf16_f32 v103, v102, v103
	v_pk_mul_f32 v[100:101], v[100:101], v[104:105]
	s_nop 0
	s_nop 0
	v_pk_mul_f32 v[100:101], v[100:101], v[150:151]
	v_mov_b32_dpp v104, v64 row_shr:1 row_mask:0xf bank_mask:0xf bound_ctrl:1
	v_mov_b32_dpp v105, v64 row_shr:2 row_mask:0xf bank_mask:0xf bound_ctrl:1
	v_cndmask_b32_e64 v104, v104, v108, s[6:7]
	v_cndmask_b32_e64 v108, v105, v204, s[4:5]
	v_cvt_pk_bf16_f32 v102, v100, v101
	v_mov_b32_dpp v105, v65 row_shr:1 row_mask:0xf bank_mask:0xf bound_ctrl:1
	v_cndmask_b32_e64 v105, v105, v112, s[6:7]
	v_pk_fma_f32 v[64:65], v[64:65], v[88:89], v[92:93]
	s_nop 0
	v_pk_fma_f32 v[64:65], v[84:85], v[104:105], v[64:65]
	v_mul_f32_e32 v104, 0xbfb8aa3b, v128
	v_mul_f32_e32 v105, 0xbfb8aa3b, v129
	v_exp_f32_e32 v104, v104
	v_exp_f32_e32 v105, v105
	v_mov_b32_dpp v112, v66 row_shr:1 row_mask:0xf bank_mask:0xf bound_ctrl:1
	v_cndmask_b32_e64 v112, v112, v114, s[6:7]
	v_cndmask_b32_e64 v114, v113, v206, s[4:5]
	s_nop 0
	v_add_f32_e32 v104, 1.0, v104
	v_add_f32_e32 v105, 1.0, v105
	v_mov_b32_dpp v113, v67 row_shr:1 row_mask:0xf bank_mask:0xf bound_ctrl:1
	v_mov_b32_dpp v144, v207 row_shl:1 row_mask:0xf bank_mask:0xf bound_ctrl:1
	v_rcp_f32_e32 v104, v104
	v_rcp_f32_e32 v105, v105
	v_cndmask_b32_e64 v113, v113, v144, s[6:7]
	v_pk_fma_f32 v[66:67], v[66:67], v[90:91], v[94:95]
	v_pk_fma_f32 v[64:65], v[68:69], v[108:109], v[64:65]
	v_pk_fma_f32 v[66:67], v[86:87], v[112:113], v[66:67]
	v_pk_mul_f32 v[104:105], v[128:129], v[104:105]
	v_pk_fma_f32 v[66:67], v[70:71], v[114:115], v[66:67]
	v_lshlrev_b32_e32 v100, 1, v175
	v_mov_b32_e32 v101, v19
	v_pk_mul_f32 v[64:65], v[104:105], v[64:65]
	s_nop 0
	v_cvt_pk_bf16_f32 v150, v64, v65
	v_mul_f32_e32 v64, 0xbfb8aa3b, v130
	v_mul_f32_e32 v65, 0xbfb8aa3b, v131
	v_exp_f32_e32 v64, v64
	v_exp_f32_e32 v65, v65
	v_add_f32_e32 v64, 1.0, v64
	v_add_f32_e32 v65, 1.0, v65
	v_rcp_f32_e32 v64, v64
	v_rcp_f32_e32 v65, v65
	s_nop 0
	v_pk_mul_f32 v[64:65], v[130:131], v[64:65]
	s_nop 0
	v_pk_mul_f32 v[64:65], v[64:65], v[66:67]
	s_nop 0
	v_cvt_pk_bf16_f32 v151, v64, v65
	v_lshl_add_u64 v[64:65], s[70:71], 0, v[18:19]
	v_lshl_add_u64 v[114:115], v[64:65], 0, v[100:101]
	global_store_dwordx4 v[114:115], v[148:151], off
	s_nop 0
	s_nop 0
	s_nop 0
	v_mov_b32_dpp v18, v60 row_shr:1 row_mask:0xf bank_mask:0xf bound_ctrl:1
	v_mov_b32_dpp v65, v60 row_shr:2 row_mask:0xf bank_mask:0xf bound_ctrl:1
	v_mov_b32_dpp v64, v208 row_shl:1 row_mask:0xf bank_mask:0xf bound_ctrl:1
	v_cndmask_b32_e64 v64, v18, v64, s[6:7]
	v_cndmask_b32_e64 v66, v65, v208, s[4:5]
	v_mov_b32_dpp v18, v61 row_shr:1 row_mask:0xf bank_mask:0xf bound_ctrl:1
	v_mov_b32_dpp v65, v209 row_shl:1 row_mask:0xf bank_mask:0xf bound_ctrl:1
	v_cndmask_b32_e64 v65, v18, v65, s[6:7]
	v_mov_b32_dpp v101, v62 row_shr:2 row_mask:0xf bank_mask:0xf
	v_mov_b32_dpp v100, v210 row_shl:1 row_mask:0xf bank_mask:0xf bound_ctrl:1
	v_mov_b32_dpp v18, v62 row_shr:1 row_mask:0xf bank_mask:0xf bound_ctrl:1
	v_cndmask_b32_e64 v100, v18, v100, s[6:7]
	v_cndmask_b32_e64 v104, v101, v210, s[4:5]
	v_mov_b32_dpp v18, v63 row_shr:1 row_mask:0xf bank_mask:0xf bound_ctrl:1
	v_mov_b32_dpp v101, v211 row_shl:1 row_mask:0xf bank_mask:0xf bound_ctrl:1
	v_mov_b32_dpp v67, v61 row_shr:2 row_mask:0xf bank_mask:0xf bound_ctrl:1
; __device__ __forceinline__ unsigned cvt_pk_bf16(float lo, float hi) { const bf16x2_t r = __builtin_convertvector((f32x2){lo, hi}, bf16x2_t); return __builtin_bit_cast(unsigned, r); }
; __device__ __forceinline__ float silu_f(float x) { return x * __builtin_amdgcn_rcpf(1.0f + __expf(-x)); }
;     __device__ __forceinline__ void sample(f32x4 (&acc)[2][2][4][2], const Unit& u, int row0t, int wr, int wc, int fr, int fq) const {
;     ...
;             for (int k = 0; k < 4; ++k) { pv[k] = (f32x4){0.f, 0.f, 0.f, 0.f}; if (t < 2) pv[k] = *(const f32x4*)((const char*)st + stoff + (unsigned)(((16 * ai + 2 * (mp + k)) * 2 * DFF2 + DFF + 4 * n) * 4)); }
; #pragma unroll
;             for (int k = 0; k < 4; ++k) { const int m = mp + k;
;                 const f32x4 uu = conv4s(acc[ai][1][m][n], pv[k], t, w0, w1, w2, bsv);
;                 const f32x4 ua = acc[ai][0][m][n];
;                 u32x2 w; w.x = cvt_pk_bf16(silu_f(ua[0]) * uu[0], silu_f(ua[1]) * uu[1]); w.y = cvt_pk_bf16(silu_f(ua[2]) * uu[2], silu_f(ua[3]) * uu[3]);
;                 if ((step & 1) == 0) pend[m] = w;
;                 else { u32x4 o; if (n == 1) { o.x = pend[m].x; o.y = pend[m].y; o.z = w.x; o.w = w.y; } else { o.x = w.x; o.y = w.y; o.z = pend[m].x; o.w = pend[m].y; }
;                     *(u32x4*)((char*)act + rowoff0 + (unsigned)((ai * HALF + m * 16) * DFF * 2) + (unsigned)(ca * 2)) = o; }
	v_cndmask_b32_e64 v101, v18, v101, s[6:7]
	v_pk_fma_f32 v[60:61], v[60:61], v[88:89], v[92:93]
	v_mul_f32_e32 v18, 0xbfb8aa3b, v124
	v_pk_fma_f32 v[60:61], v[84:85], v[64:65], v[60:61]
	v_exp_f32_e32 v18, v18
	v_mul_f32_e32 v64, 0xbfb8aa3b, v125
	v_exp_f32_e32 v65, v64
	v_cndmask_b32_e64 v67, v67, v209, s[4:5]
	v_add_f32_e32 v18, 1.0, v18
	v_rcp_f32_e32 v64, v18
	v_add_f32_e32 v18, 1.0, v65
	v_mul_f32_e32 v65, 0xbfb8aa3b, v126
	v_pk_fma_f32 v[60:61], v[68:69], v[66:67], v[60:61]
	v_exp_f32_e32 v66, v65
	v_mul_f32_e32 v65, 0xbfb8aa3b, v127
	v_exp_f32_e32 v67, v65
	s_nop 0
	v_rcp_f32_e32 v65, v18
	v_add_f32_e32 v18, 1.0, v66
	v_mov_b32_dpp v105, v63 row_shr:2 row_mask:0xf bank_mask:0xf bound_ctrl:1
	v_pk_fma_f32 v[62:63], v[62:63], v[90:91], v[94:95]
	v_rcp_f32_e32 v66, v18
	v_add_f32_e32 v18, 1.0, v67
	v_cndmask_b32_e64 v105, v105, v211, s[4:5]
	v_pk_fma_f32 v[62:63], v[86:87], v[100:101], v[62:63]
	v_rcp_f32_e32 v67, v18
	v_pk_fma_f32 v[62:63], v[70:71], v[104:105], v[62:63]
	v_pk_mul_f32 v[64:65], v[124:125], v[64:65]
	s_mov_b32 s2, 0x16000
	v_pk_mul_f32 v[60:61], v[64:65], v[60:61]
	s_nop 0
	v_cvt_pk_bf16_f32 v112, v60, v61
	v_pk_mul_f32 v[60:61], v[126:127], v[66:67]
	s_nop 0
	v_pk_mul_f32 v[60:61], v[60:61], v[62:63]
	s_nop 0
	v_cvt_pk_bf16_f32 v113, v60, v61
	v_add_co_u32_e32 v60, vcc, s2, v114
	s_nop 1
	v_addc_co_u32_e32 v61, vcc, 0, v115, vcc
	global_store_dwordx4 v[60:61], v[110:113], off
	s_nop 0
	s_nop 0
	s_nop 0
	v_mov_b32_dpp v18, v56 row_shr:1 row_mask:0xf bank_mask:0xf bound_ctrl:1
	v_mov_b32_dpp v61, v56 row_shr:2 row_mask:0xf bank_mask:0xf bound_ctrl:1
	v_mov_b32_dpp v60, v212 row_shl:1 row_mask:0xf bank_mask:0xf bound_ctrl:1
	v_cndmask_b32_e64 v60, v18, v60, s[6:7]
	v_cndmask_b32_e64 v62, v61, v212, s[4:5]
	v_mov_b32_dpp v18, v57 row_shr:1 row_mask:0xf bank_mask:0xf bound_ctrl:1
	v_mov_b32_dpp v61, v213 row_shl:1 row_mask:0xf bank_mask:0xf bound_ctrl:1
	v_cndmask_b32_e64 v61, v18, v61, s[6:7]
	v_mov_b32_dpp v65, v58 row_shr:2 row_mask:0xf bank_mask:0xf bound_ctrl:1
	v_mov_b32_dpp v18, v58 row_shr:1 row_mask:0xf bank_mask:0xf bound_ctrl:1
	v_mov_b32_dpp v64, v214 row_shl:1 row_mask:0xf bank_mask:0xf bound_ctrl:1
	v_cndmask_b32_e64 v64, v18, v64, s[6:7]
	v_cndmask_b32_e64 v66, v65, v214, s[4:5]
	v_mov_b32_dpp v18, v59 row_shr:1 row_mask:0xf bank_mask:0xf bound_ctrl:1
	v_mov_b32_dpp v65, v215 row_shl:1 row_mask:0xf bank_mask:0xf bound_ctrl:1
	v_mov_b32_dpp v63, v57 row_shr:2 row_mask:0xf bank_mask:0xf bound_ctrl:1
	v_cndmask_b32_e64 v65, v18, v65, s[6:7]
	v_pk_fma_f32 v[56:57], v[56:57], v[88:89], v[92:93]
	v_mul_f32_e32 v18, 0xbfb8aa3b, v120
	v_pk_fma_f32 v[56:57], v[84:85], v[60:61], v[56:57]
	v_exp_f32_e32 v18, v18
	v_mul_f32_e32 v60, 0xbfb8aa3b, v121
	v_exp_f32_e32 v61, v60
	v_cndmask_b32_e64 v63, v63, v213, s[4:5]
	v_add_f32_e32 v18, 1.0, v18
	v_rcp_f32_e32 v60, v18
	v_add_f32_e32 v18, 1.0, v61
	v_mul_f32_e32 v61, 0xbfb8aa3b, v122
	v_pk_fma_f32 v[56:57], v[68:69], v[62:63], v[56:57]
	v_exp_f32_e32 v62, v61
	v_mul_f32_e32 v61, 0xbfb8aa3b, v123
	v_exp_f32_e32 v63, v61
	s_nop 0
	v_rcp_f32_e32 v61, v18
	v_add_f32_e32 v18, 1.0, v62
	v_mov_b32_dpp v67, v59 row_shr:2 row_mask:0xf bank_mask:0xf bound_ctrl:1
	v_pk_fma_f32 v[58:59], v[58:59], v[90:91], v[94:95]
	v_rcp_f32_e32 v62, v18
	v_add_f32_e32 v18, 1.0, v63
	v_cndmask_b32_e64 v67, v67, v215, s[4:5]
	v_pk_fma_f32 v[58:59], v[86:87], v[64:65], v[58:59]
	v_rcp_f32_e32 v63, v18
	v_pk_fma_f32 v[58:59], v[70:71], v[66:67], v[58:59]
	v_pk_mul_f32 v[60:61], v[120:121], v[60:61]
	s_mov_b32 s2, 0x2c000
	v_pk_mul_f32 v[56:57], v[60:61], v[56:57]
	s_nop 0
	v_cvt_pk_bf16_f32 v108, v56, v57
	v_pk_mul_f32 v[56:57], v[122:123], v[62:63]
	s_nop 0
	v_pk_mul_f32 v[56:57], v[56:57], v[58:59]
	s_nop 0
	v_cvt_pk_bf16_f32 v109, v56, v57
	v_add_co_u32_e32 v56, vcc, s2, v114
	s_nop 1
	v_addc_co_u32_e32 v57, vcc, 0, v115, vcc
	global_store_dwordx4 v[56:57], v[106:109], off
	s_nop 0
	s_nop 0
	s_nop 0
	v_mov_b32_dpp v18, v32 row_shr:1 row_mask:0xf bank_mask:0xf bound_ctrl:1
	v_mov_b32_dpp v57, v32 row_shr:2 row_mask:0xf bank_mask:0xf bound_ctrl:1
	v_mov_b32_dpp v56, v216 row_shl:1 row_mask:0xf bank_mask:0xf bound_ctrl:1
	v_cndmask_b32_e64 v56, v18, v56, s[6:7]
	v_cndmask_b32_e64 v58, v57, v216, s[4:5]
	v_mov_b32_dpp v18, v33 row_shr:1 row_mask:0xf bank_mask:0xf bound_ctrl:1
	v_mov_b32_dpp v57, v217 row_shl:1 row_mask:0xf bank_mask:0xf bound_ctrl:1
	v_cndmask_b32_e64 v57, v18, v57, s[6:7]
	v_mov_b32_dpp v61, v34 row_shr:2 row_mask:0xf bank_mask:0xf bound_ctrl:1
	v_mov_b32_dpp v18, v34 row_shr:1 row_mask:0xf bank_mask:0xf bound_ctrl:1
	v_mov_b32_dpp v60, v218 row_shl:1 row_mask:0xf bank_mask:0xf bound_ctrl:1
	v_cndmask_b32_e64 v60, v18, v60, s[6:7]
	v_cndmask_b32_e64 v62, v61, v218, s[4:5]
	v_mov_b32_dpp v18, v35 row_shr:1 row_mask:0xf bank_mask:0xf bound_ctrl:1
	v_mov_b32_dpp v61, v219 row_shl:1 row_mask:0xf bank_mask:0xf bound_ctrl:1
	v_mov_b32_dpp v59, v33 row_shr:2 row_mask:0xf bank_mask:0xf bound_ctrl:1
	v_cndmask_b32_e64 v61, v18, v61, s[6:7]
	v_pk_fma_f32 v[32:33], v[32:33], v[88:89], v[92:93]
	v_mul_f32_e32 v18, 0xbfb8aa3b, v116
	v_pk_fma_f32 v[32:33], v[84:85], v[56:57], v[32:33]
	v_exp_f32_e32 v18, v18
	v_mul_f32_e32 v56, 0xbfb8aa3b, v117
	v_exp_f32_e32 v57, v56
	v_cndmask_b32_e64 v59, v59, v217, s[4:5]
	v_add_f32_e32 v18, 1.0, v18
	v_rcp_f32_e32 v56, v18
	v_add_f32_e32 v18, 1.0, v57
	v_mul_f32_e32 v57, 0xbfb8aa3b, v118
	v_pk_fma_f32 v[32:33], v[68:69], v[58:59], v[32:33]
	v_exp_f32_e32 v58, v57
	v_mul_f32_e32 v57, 0xbfb8aa3b, v119
	v_exp_f32_e32 v59, v57
	s_nop 0
	v_rcp_f32_e32 v57, v18
	v_add_f32_e32 v18, 1.0, v58
	v_mov_b32_dpp v63, v35 row_shr:2 row_mask:0xf bank_mask:0xf bound_ctrl:1
	v_pk_fma_f32 v[34:35], v[34:35], v[90:91], v[94:95]
	v_rcp_f32_e32 v58, v18
	v_add_f32_e32 v18, 1.0, v59
	v_cndmask_b32_e64 v63, v63, v219, s[4:5]
	v_pk_fma_f32 v[34:35], v[86:87], v[60:61], v[34:35]
	v_rcp_f32_e32 v59, v18
	v_pk_fma_f32 v[34:35], v[70:71], v[62:63], v[34:35]
	v_pk_mul_f32 v[56:57], v[116:117], v[56:57]
	s_nop 0
	v_pk_mul_f32 v[32:33], v[56:57], v[32:33]
	s_nop 0
	v_cvt_pk_bf16_f32 v104, v32, v33
	v_pk_mul_f32 v[32:33], v[118:119], v[58:59]
	s_nop 0
	v_pk_mul_f32 v[32:33], v[32:33], v[34:35]
	s_nop 0
	v_cvt_pk_bf16_f32 v105, v32, v33
	v_add_co_u32_e32 v32, vcc, 0x42000, v114
	s_nop 1
	v_addc_co_u32_e32 v33, vcc, 0, v115, vcc
	global_store_dwordx4 v[32:33], v[102:105], off
	v_mov_b32_e32 v56, 0
	v_mov_b32_e32 v64, 0
	v_mov_b32_e32 v65, 0
	v_mov_b32_e32 v66, 0
	v_mov_b32_e32 v67, 0
	v_mov_b32_e32 v57, 0
	v_mov_b32_e32 v58, 0
	v_mov_b32_e32 v59, 0
	v_mov_b32_e32 v32, 0
	v_mov_b32_e32 v60, 0
	v_mov_b32_e32 v61, 0
	v_mov_b32_e32 v62, 0
	v_mov_b32_e32 v63, 0
	v_mov_b32_e32 v33, 0
	v_mov_b32_e32 v34, 0
	v_mov_b32_e32 v35, 0
	s_nop 0
	s_nop 0
	v_mov_b32_e32 v100, v19
	v_mov_b32_dpp v18, v52 row_shr:1 row_mask:0xf bank_mask:0xf bound_ctrl:1
	v_mov_b32_dpp v101, v52 row_shr:2 row_mask:0xf bank_mask:0xf bound_ctrl:1
	s_waitcnt vmcnt(4)
;     __device__ __forceinline__ void sample(f32x4 (&acc)[2][2][4][2], const Unit& u, int row0t, int wr, int wc, int fr, int fq) const {
;     ...
;             for (int mp = 0; mp < 4; mp += 4) {
;             f32x4 pv[4];
; #pragma unroll
;             for (int k = 0; k < 4; ++k) { pv[k] = (f32x4){0.f, 0.f, 0.f, 0.f}; if (t < 2) pv[k] = *(const f32x4*)((const char*)st + stoff + (unsigned)(((16 * ai + 2 * (mp + k)) * 2 * DFF2 + DFF + 4 * n) * 4)); }
	v_mov_b32_e32 v204, 0
	v_mov_b32_e32 v205, 0
	v_mov_b32_e32 v206, 0
	v_mov_b32_e32 v207, 0
	v_mov_b32_e32 v208, 0
	v_mov_b32_e32 v209, 0
	v_mov_b32_e32 v210, 0
	v_mov_b32_e32 v211, 0
	v_mov_b32_e32 v212, 0
	v_mov_b32_e32 v213, 0
	v_mov_b32_e32 v214, 0
	v_mov_b32_e32 v215, 0
	v_mov_b32_e32 v216, 0
	v_mov_b32_e32 v217, 0
	v_mov_b32_e32 v218, 0
	v_mov_b32_e32 v219, 0
	s_and_saveexec_b64 s[100:101], s[4:5]
	s_cbranch_execz .Lspp_7
	s_mov_b64 s[98:99], 0xb2c00
	v_lshl_add_u64 v[194:195], v[172:173], 0, s[98:99]
	global_load_dwordx4 v[204:207], v[194:195], off
	s_mov_b64 s[98:99], 0xc8c00
	v_lshl_add_u64 v[194:195], v[172:173], 0, s[98:99]
	global_load_dwordx4 v[208:211], v[194:195], off
	s_mov_b64 s[98:99], 0xdec00
	v_lshl_add_u64 v[194:195], v[172:173], 0, s[98:99]
	global_load_dwordx4 v[212:215], v[194:195], off
	s_mov_b64 s[98:99], 0xf4c00
	v_lshl_add_u64 v[194:195], v[172:173], 0, s[98:99]
	global_load_dwordx4 v[216:219], v[194:195], off
